# ml_seq: + wvl reads first, vT/vwT swizzle, hoisted S.V operand reads, early global prefetch issue
# baseline (speedup 1.0000x reference)
.LBB0_789:
	s_or_b64 exec, exec, s[4:5]
	v_lshlrev_b32_e32 v62, 3, v57
	v_or_b32_e32 v32, v62, v32
	v_mul_u32_u24_e32 v53, 0x208, v32
	s_movk_i32 s8, 0x90
	s_lshl_b32 s19, s20, 7
	v_add_u32_e32 v64, v53, v52
	v_mul_lo_u32 v65, v140, s8
	s_movk_i32 s8, 0x410
	v_lshl_add_u32 v66, v64, 1, 0
	v_lshlrev_b32_e32 v64, 1, v56
	v_mul_lo_u32 v56, v140, s8
	s_add_u32 s8, s10, s80
	v_and_b32_e32 v154, 15, v54
	v_lshlrev_b32_e32 v63, 5, v60
	s_movk_i32 s4, 0x100
	v_readlane_b32 s22, v255, 13
	s_addc_u32 s9, s11, 0
	s_lshl_b64 s[6:7], s[6:7], 1
	v_readlane_b32 s24, v255, 15
	v_lshlrev_b32_e32 v68, 1, v54
	v_readlane_b32 s25, v255, 16
	v_lshlrev_b32_e32 v61, 2, v55
	v_and_or_b32 v155, v63, 32, v154
	v_cmp_gt_i32_e32 vcc, s4, v54
	v_and_b32_e32 v63, 0xffffffc0, v54
	v_add3_u32 v156, s22, v65, v64
	v_mov_b32_e32 v65, v0
	s_add_u32 s20, s12, s6
	v_lshl_add_u64 v[148:149], v[58:59], 1, s[14:15]
	v_lshl_add_u32 v158, v54, 2, s24
	v_add_u32_e32 v58, s25, v68
	v_lshrrev_b32_e32 v54, 3, v54
	v_add3_u32 v157, 0, v56, v64
	v_lshl_add_u64 v[144:145], s[8:9], 0, v[64:65]
	s_addc_u32 s21, s13, s7
	v_lshlrev_b32_e32 v64, 1, v61
	v_lshlrev_b32_e32 v61, 1, v62
	v_add_u32_e32 v159, 0xffffff80, v58
	v_mul_u32_u24_e32 v58, 0x410, v155
	v_and_b32_e32 v54, 16, v54
	v_lshl_add_u64 v[146:147], s[20:21], 0, v[64:65]
	v_lshlrev_b32_e32 v65, 1, v63
	v_readlane_b32 s6, v255, 9
	v_add3_u32 v160, 0, v58, v61
	v_or_b32_e32 v58, v54, v154
	v_add_u32_e32 v67, s6, v65
	v_cmp_gt_i32_e64 s[6:7], 4, v60
	v_mul_u32_u24_e32 v60, 0x410, v58
	v_mul_u32_u24_e32 v69, 0x90, v58
	v_mul_u32_u24_e32 v58, 0x90, v155
	v_add3_u32 v161, s22, v58, v61
	v_lshlrev_b32_e32 v58, 1, v54
	v_mov_b32_e32 v59, v0
	v_lshl_add_u64 v[58:59], s[20:21], 0, v[58:59]
	v_mul_u32_u24_e32 v54, 0x90, v154
	v_readlane_b32 s21, v255, 17
	v_lshlrev_b32_e32 v56, 6, v55
	v_readlane_b32 s23, v255, 14
	v_lshrrev_b32_e32 v194, 2, v154
	v_xor_b32_e32 v194, v194, v57
	v_lshlrev_b32_e32 v194, 4, v194
	v_add3_u32 v162, s21, v54, v194
	v_mul_u32_u24_e32 v54, 0x120, v55
	v_and_b32_e32 v195, 3, v55
	v_lshlrev_b32_e32 v195, 3, v195
	v_xor_b32_e32 v195, v195, v140
	v_add_lshl_u32 v54, v54, v195, 1
	v_add_u32_e32 v55, 0x90, v54
	v_add_u32_e32 v165, s23, v54
	v_add_u32_e32 v166, s21, v54
	v_add_u32_e32 v167, s23, v55
	v_add_u32_e32 v168, s21, v55
	v_add_u32_e32 v55, 0x120, v54
	v_add_u32_e32 v54, 0x1b0, v54
	v_add_u32_e32 v171, s23, v54
	v_add_u32_e32 v172, s21, v54
	v_mul_u32_u24_e32 v54, 0x410, v154
	v_add3_u32 v176, v67, v62, v54
	v_lshlrev_b32_e32 v54, 4, v57
	v_cmp_eq_u32_e64 s[4:5], 64, v63
	v_add_u32_e32 v64, s23, v194
	v_mov_b32_e32 v63, v0
	v_readlane_b32 s20, v255, 10
	v_add_u32_e32 v169, s23, v55
	v_add_u32_e32 v170, s21, v55
	v_or_b32_e32 v174, 16, v155
	v_and_b32_e32 v55, 0xffffff80, v68
	v_add_u32_e32 v177, 0, v54
	v_add3_u32 v190, v60, v54, 0
	v_mov_b32_e32 v54, 0
	v_add_u32_e32 v56, 0, v56
	s_mov_b32 s30, 0
	v_mov_b32_e32 v48, v0
	v_mov_b32_e32 v49, v0
	v_mov_b32_e32 v44, v0
	v_mov_b32_e32 v45, v0
	v_mov_b32_e32 v32, v0
	v_mov_b32_e32 v33, v0
	v_mov_b32_e32 v52, v0
	v_mov_b32_e32 v53, v0
	v_cmp_eq_u32_e64 s[8:9], 0, v154
	v_lshl_add_u64 v[150:151], v[58:59], 0, v[62:63]
	v_add_u32_e32 v163, s25, v61
	v_add3_u32 v164, s20, v65, v62
	v_lshl_add_u32 v173, v155, 2, s24
	v_lshl_add_u32 v175, v174, 2, s24
	s_mov_b64 s[20:21], 0
	v_add_u32_e32 v191, 0x25980, v56
	v_add_u32_e32 v192, v64, v69
	v_add_u32_e32 v193, v66, v55
	v_mov_b32_e32 v55, v54
	v_mov_b32_e32 v56, v54
	v_mov_b32_e32 v57, v54
	v_mov_b32_e32 v58, v54
	v_mov_b32_e32 v59, v54
	v_mov_b32_e32 v60, v54
	v_mov_b32_e32 v61, v54
	v_mov_b32_e32 v62, v54
	v_mov_b32_e32 v63, v54
	v_mov_b32_e32 v64, v54
	v_mov_b32_e32 v65, v54
	v_mov_b32_e32 v66, v54
	v_mov_b32_e32 v67, v54
	v_mov_b32_e32 v68, v54
	v_mov_b32_e32 v69, v54
	v_mov_b32_e32 v90, v54
	v_mov_b32_e32 v91, v54
	v_mov_b32_e32 v92, v54
	v_mov_b32_e32 v93, v54
	v_mov_b32_e32 v78, v54
	v_mov_b32_e32 v79, v54
	v_mov_b32_e32 v80, v54
	v_mov_b32_e32 v81, v54
	v_mov_b32_e32 v70, v54
	v_mov_b32_e32 v71, v54
	v_mov_b32_e32 v72, v54
	v_mov_b32_e32 v73, v54
	v_mov_b32_e32 v74, v54
	v_mov_b32_e32 v75, v54
	v_mov_b32_e32 v76, v54
	v_mov_b32_e32 v77, v54
	v_mov_b32_e32 v82, v54
	v_mov_b32_e32 v83, v54
	v_mov_b32_e32 v84, v54
	v_mov_b32_e32 v85, v54
	v_mov_b32_e32 v86, v54
	v_mov_b32_e32 v87, v54
	v_mov_b32_e32 v88, v54
	v_mov_b32_e32 v89, v54
	v_mov_b32_e32 v94, v54
	v_mov_b32_e32 v95, v54
	v_mov_b32_e32 v96, v54
	v_mov_b32_e32 v97, v54
	v_mov_b32_e32 v98, v54
	v_mov_b32_e32 v99, v54
	v_mov_b32_e32 v100, v54
	v_mov_b32_e32 v101, v54
	s_branch .LBB0_791

.LBB0_791:
	ds_read_b128 v[102:105], v191
	ds_read_b128 v[106:109], v191 offset:16
	ds_read_b128 v[110:113], v191 offset:32
	ds_read_b128 v[114:117], v191 offset:48
	s_and_saveexec_b64 s[22:23], vcc
	s_cbranch_execz .LBB0_793
	s_waitcnt vmcnt(11)
	ds_write_b32 v158, v152
.LBB0_793:
	s_or_b64 exec, exec, s[22:23]
	s_and_saveexec_b64 s[22:23], s[4:5]
	s_cbranch_execz .LBB0_795
	s_waitcnt vmcnt(11)
	v_cvt_pk_bf16_f32 v118, v152, s0
	ds_write_b16 v159, v118
.LBB0_795:
	s_or_b64 exec, exec, s[22:23]
	s_waitcnt vmcnt(0)
	ds_write_b128 v156, v[38:41]
	ds_write_b128 v157, v[2:5]
	ds_write_b128 v157, v[6:9] offset:128
	ds_write_b128 v157, v[10:13] offset:256
	ds_write_b128 v157, v[14:17] offset:384
	ds_write_b128 v157, v[18:21] offset:512
	ds_write_b128 v157, v[22:25] offset:640
	ds_write_b128 v157, v[26:29] offset:768
	ds_write_b128 v157, v[34:37] offset:896
	s_add_i32 s29, s30, 1
	s_cmpk_eq_i32 s30, 0x7f
	s_cbranch_scc1 .Lmlq_noearly
	s_lshl_b32 s23, s29, 6
	s_add_i32 s22, s29, s19
	s_add_i32 s80, s23, s18
	s_mov_b32 s23, s81
	s_lshl_b64 s[24:25], s[22:23], 10
	s_add_u32 s24, s27, s24
	s_addc_u32 s25, s28, s25
	v_lshl_add_u64 v[34:35], s[80:81], 0, v[140:141]
	v_lshl_add_u64 v[228:229], v[140:141], 2, s[24:25]
	v_lshlrev_b64 v[4:5], 12, v[34:35]
	v_lshl_add_u64 v[36:37], v[144:145], 0, v[4:5]
	global_load_dword v152, v1, s[24:25]
	global_load_dwordx4 v[2:5], v[36:37], off
	global_load_dwordx4 v[6:9], v[36:37], off offset:128
	global_load_dwordx4 v[10:13], v[36:37], off offset:256
	global_load_dwordx4 v[14:17], v[36:37], off offset:384
	global_load_dwordx4 v[18:21], v[36:37], off offset:512
	global_load_dwordx4 v[22:25], v[36:37], off offset:640
	global_load_dwordx4 v[26:29], v[36:37], off offset:768
	v_lshlrev_b64 v[34:35], 13, v[34:35]
	v_lshl_add_u64 v[230:231], v[146:147], 0, v[34:35]
	s_lshl_b64 s[22:23], s[22:23], 13
	global_load_dwordx4 v[34:37], v[36:37], off offset:896
	v_lshl_add_u64 v[38:39], v[148:149], 0, s[22:23]
	global_load_dwordx4 v[38:41], v[38:39], off
.Lmlq_noearly:
	v_and_b32_e32 v119, 0xffff0000, v142
	v_lshlrev_b32_e32 v118, 16, v142
	v_lshlrev_b32_e32 v120, 16, v143
	s_waitcnt lgkmcnt(9)
	v_mul_f32_e32 v106, v106, v119
	v_fmac_f32_e32 v106, v102, v118
	v_and_b32_e32 v121, 0xffff0000, v143
	v_fmac_f32_e32 v106, v110, v120
	v_fmac_f32_e32 v106, v114, v121
	v_cvt_pk_bf16_f32 v102, v106, s0
	ds_write_b16 v165, v102
	v_mul_f32_e32 v102, v153, v106
	v_cvt_pk_bf16_f32 v102, v102, s0
	ds_write_b16 v166, v102
	v_mul_f32_e32 v102, v107, v119
	v_fmac_f32_e32 v102, v103, v118
	v_fmac_f32_e32 v102, v111, v120
	v_fmac_f32_e32 v102, v115, v121
	v_cvt_pk_bf16_f32 v103, v102, s0
	v_mul_f32_e32 v102, v153, v102
	v_cvt_pk_bf16_f32 v102, v102, s0
	ds_write_b16 v168, v102
	v_mul_f32_e32 v102, v108, v119
	v_fmac_f32_e32 v102, v104, v118
	v_fmac_f32_e32 v102, v112, v120
	v_fmac_f32_e32 v102, v116, v121
	ds_write_b16 v167, v103
	v_cvt_pk_bf16_f32 v103, v102, s0
	v_mul_f32_e32 v102, v153, v102
	v_cvt_pk_bf16_f32 v102, v102, s0
	ds_write_b16 v170, v102
	v_mul_f32_e32 v102, v109, v119
	v_fmac_f32_e32 v102, v105, v118
	v_fmac_f32_e32 v102, v113, v120
	v_fmac_f32_e32 v102, v117, v121
	ds_write_b16 v169, v103
	v_cvt_pk_bf16_f32 v103, v102, s0
	v_mul_f32_e32 v102, v153, v102
	v_cvt_pk_bf16_f32 v102, v102, s0
	ds_write_b16 v171, v103
	ds_write_b16 v172, v102
	s_cmpk_eq_i32 s30, 0x7f
	s_cbranch_scc1 .Lmlq_nolate
	global_load_dword v153, v[228:229], off offset:256
	global_load_dwordx2 v[142:143], v[230:231], off
.Lmlq_nolate:
	s_waitcnt lgkmcnt(0)
	s_barrier
.LBB0_797:
	s_and_saveexec_b64 s[22:23], s[6:7]
	s_cbranch_execz .LBB0_805
	v_cndmask_b32_e64 v102, 0, 1, s[20:21]
	s_movk_i32 s24, 0x440
	v_mul_lo_u32 v103, v102, s24
	s_mov_b32 s24, 0x8200
	v_mul_lo_u32 v102, v102, s24
	v_add_u32_e32 v227, v177, v103
	v_add_u32_e32 v226, v190, v102
	v_add_u32_e32 v227, 0x20800, v227
	v_add_u32_e32 v226, 0x10400, v226
	v_mov_b32_e32 v130, 0
	v_mov_b32_e32 v131, 0
	v_mov_b32_e32 v132, 0
	v_mov_b32_e32 v133, 0
	v_mov_b32_e32 v206, 0
	v_mov_b32_e32 v207, 0
	v_mov_b32_e32 v208, 0
	v_mov_b32_e32 v209, 0
	v_mov_b32_e32 v222, 0
	v_mov_b32_e32 v223, 0
	v_mov_b32_e32 v224, 0
	v_mov_b32_e32 v225, 0
	ds_read_b128 v[118:121], v160
	ds_read_b128 v[122:125], v160 offset:16640
	ds_read_b128 v[126:129], v226
	s_and_saveexec_b64 s[24:25], s[8:9]
	ds_read_b128 v[130:133], v227
	s_or_b64 exec, exec, s[24:25]
	ds_read_b128 v[194:197], v160 offset:64
	ds_read_b128 v[198:201], v160 offset:16704
	ds_read_b128 v[202:205], v226 offset:64
	s_and_saveexec_b64 s[24:25], s[8:9]
	ds_read_b128 v[206:209], v227 offset:64
	s_or_b64 exec, exec, s[24:25]
	v_mov_b32_e32 v102, 0
	v_mov_b32_e32 v103, 0
	v_mov_b32_e32 v104, 0
	v_mov_b32_e32 v105, 0
	v_mov_b32_e32 v106, 0
	v_mov_b32_e32 v107, 0
	v_mov_b32_e32 v108, 0
	v_mov_b32_e32 v109, 0
	v_mov_b32_e32 v110, 0
	v_mov_b32_e32 v111, 0
	v_mov_b32_e32 v112, 0
	v_mov_b32_e32 v113, 0
	v_mov_b32_e32 v114, 0
	v_mov_b32_e32 v115, 0
	v_mov_b32_e32 v116, 0
	v_mov_b32_e32 v117, 0
	s_waitcnt lgkmcnt(4)
	v_mfma_f32_16x16x32_bf16 v[110:113], v[126:129], v[118:121], v[110:113]
	v_mfma_f32_16x16x32_bf16 v[114:117], v[130:133], v[118:121], v[114:117]
	v_mfma_f32_16x16x32_bf16 v[102:105], v[126:129], v[122:125], v[102:105]
	v_mfma_f32_16x16x32_bf16 v[106:109], v[130:133], v[122:125], v[106:109]
	ds_read_b128 v[210:213], v160 offset:128
	ds_read_b128 v[214:217], v160 offset:16768
	ds_read_b128 v[218:221], v226 offset:128
	s_and_saveexec_b64 s[24:25], s[8:9]
	ds_read_b128 v[222:225], v227 offset:128
	s_or_b64 exec, exec, s[24:25]
	s_waitcnt lgkmcnt(4)
	v_mfma_f32_16x16x32_bf16 v[110:113], v[202:205], v[194:197], v[110:113]
	v_mfma_f32_16x16x32_bf16 v[114:117], v[206:209], v[194:197], v[114:117]
	v_mfma_f32_16x16x32_bf16 v[102:105], v[202:205], v[198:201], v[102:105]
	v_mfma_f32_16x16x32_bf16 v[106:109], v[206:209], v[198:201], v[106:109]
	ds_read_b128 v[118:121], v160 offset:192
	ds_read_b128 v[122:125], v160 offset:16832
	ds_read_b128 v[126:129], v226 offset:192
	s_and_saveexec_b64 s[24:25], s[8:9]
	ds_read_b128 v[130:133], v227 offset:192
	s_or_b64 exec, exec, s[24:25]
	s_waitcnt lgkmcnt(4)
	v_mfma_f32_16x16x32_bf16 v[110:113], v[218:221], v[210:213], v[110:113]
	v_mfma_f32_16x16x32_bf16 v[114:117], v[222:225], v[210:213], v[114:117]
	v_mfma_f32_16x16x32_bf16 v[102:105], v[218:221], v[214:217], v[102:105]
	v_mfma_f32_16x16x32_bf16 v[106:109], v[222:225], v[214:217], v[106:109]
	ds_read_b128 v[194:197], v160 offset:256
	ds_read_b128 v[198:201], v160 offset:16896
	ds_read_b128 v[202:205], v226 offset:256
	s_and_saveexec_b64 s[24:25], s[8:9]
	ds_read_b128 v[206:209], v227 offset:256
	s_or_b64 exec, exec, s[24:25]
	s_waitcnt lgkmcnt(4)
	v_mfma_f32_16x16x32_bf16 v[110:113], v[126:129], v[118:121], v[110:113]
	v_mfma_f32_16x16x32_bf16 v[114:117], v[130:133], v[118:121], v[114:117]
	v_mfma_f32_16x16x32_bf16 v[102:105], v[126:129], v[122:125], v[102:105]
	v_mfma_f32_16x16x32_bf16 v[106:109], v[130:133], v[122:125], v[106:109]
	ds_read_b128 v[210:213], v160 offset:320
	ds_read_b128 v[214:217], v160 offset:16960
	ds_read_b128 v[218:221], v226 offset:320
	s_and_saveexec_b64 s[24:25], s[8:9]
	ds_read_b128 v[222:225], v227 offset:320
	s_or_b64 exec, exec, s[24:25]
	s_waitcnt lgkmcnt(4)
	v_mfma_f32_16x16x32_bf16 v[110:113], v[202:205], v[194:197], v[110:113]
	v_mfma_f32_16x16x32_bf16 v[114:117], v[206:209], v[194:197], v[114:117]
	v_mfma_f32_16x16x32_bf16 v[102:105], v[202:205], v[198:201], v[102:105]
	v_mfma_f32_16x16x32_bf16 v[106:109], v[206:209], v[198:201], v[106:109]
	ds_read_b128 v[118:121], v160 offset:384
	ds_read_b128 v[122:125], v160 offset:17024
	ds_read_b128 v[126:129], v226 offset:384
	s_and_saveexec_b64 s[24:25], s[8:9]
	ds_read_b128 v[130:133], v227 offset:384
	s_or_b64 exec, exec, s[24:25]
	s_waitcnt lgkmcnt(4)
	v_mfma_f32_16x16x32_bf16 v[110:113], v[218:221], v[210:213], v[110:113]
	v_mfma_f32_16x16x32_bf16 v[114:117], v[222:225], v[210:213], v[114:117]
	v_mfma_f32_16x16x32_bf16 v[102:105], v[218:221], v[214:217], v[102:105]
	v_mfma_f32_16x16x32_bf16 v[106:109], v[222:225], v[214:217], v[106:109]
	ds_read_b128 v[194:197], v160 offset:448
	ds_read_b128 v[198:201], v160 offset:17088
	ds_read_b128 v[202:205], v226 offset:448
	s_and_saveexec_b64 s[24:25], s[8:9]
	ds_read_b128 v[206:209], v227 offset:448
	s_or_b64 exec, exec, s[24:25]
	s_waitcnt lgkmcnt(4)
	v_mfma_f32_16x16x32_bf16 v[110:113], v[126:129], v[118:121], v[110:113]
	v_mfma_f32_16x16x32_bf16 v[114:117], v[130:133], v[118:121], v[114:117]
	v_mfma_f32_16x16x32_bf16 v[102:105], v[126:129], v[122:125], v[102:105]
	v_mfma_f32_16x16x32_bf16 v[106:109], v[130:133], v[122:125], v[106:109]
	ds_read_b128 v[210:213], v160 offset:512
	ds_read_b128 v[214:217], v160 offset:17152
	ds_read_b128 v[218:221], v226 offset:512
	s_and_saveexec_b64 s[24:25], s[8:9]
	ds_read_b128 v[222:225], v227 offset:512
	s_or_b64 exec, exec, s[24:25]
	s_waitcnt lgkmcnt(4)
	v_mfma_f32_16x16x32_bf16 v[110:113], v[202:205], v[194:197], v[110:113]
	v_mfma_f32_16x16x32_bf16 v[114:117], v[206:209], v[194:197], v[114:117]
	v_mfma_f32_16x16x32_bf16 v[102:105], v[202:205], v[198:201], v[102:105]
	v_mfma_f32_16x16x32_bf16 v[106:109], v[206:209], v[198:201], v[106:109]
	ds_read_b128 v[118:121], v160 offset:576
	ds_read_b128 v[122:125], v160 offset:17216
	ds_read_b128 v[126:129], v226 offset:576
	s_and_saveexec_b64 s[24:25], s[8:9]
	ds_read_b128 v[130:133], v227 offset:576
	s_or_b64 exec, exec, s[24:25]
	s_waitcnt lgkmcnt(4)
	v_mfma_f32_16x16x32_bf16 v[110:113], v[218:221], v[210:213], v[110:113]
	v_mfma_f32_16x16x32_bf16 v[114:117], v[222:225], v[210:213], v[114:117]
	v_mfma_f32_16x16x32_bf16 v[102:105], v[218:221], v[214:217], v[102:105]
	v_mfma_f32_16x16x32_bf16 v[106:109], v[222:225], v[214:217], v[106:109]
	ds_read_b128 v[194:197], v160 offset:640
	ds_read_b128 v[198:201], v160 offset:17280
	ds_read_b128 v[202:205], v226 offset:640
	s_and_saveexec_b64 s[24:25], s[8:9]
	ds_read_b128 v[206:209], v227 offset:640
	s_or_b64 exec, exec, s[24:25]
	s_waitcnt lgkmcnt(4)
	v_mfma_f32_16x16x32_bf16 v[110:113], v[126:129], v[118:121], v[110:113]
	v_mfma_f32_16x16x32_bf16 v[114:117], v[130:133], v[118:121], v[114:117]
	v_mfma_f32_16x16x32_bf16 v[102:105], v[126:129], v[122:125], v[102:105]
	v_mfma_f32_16x16x32_bf16 v[106:109], v[130:133], v[122:125], v[106:109]
	ds_read_b128 v[210:213], v160 offset:704
	ds_read_b128 v[214:217], v160 offset:17344
	ds_read_b128 v[218:221], v226 offset:704
	s_and_saveexec_b64 s[24:25], s[8:9]
	ds_read_b128 v[222:225], v227 offset:704
	s_or_b64 exec, exec, s[24:25]
	s_waitcnt lgkmcnt(4)
	v_mfma_f32_16x16x32_bf16 v[110:113], v[202:205], v[194:197], v[110:113]
	v_mfma_f32_16x16x32_bf16 v[114:117], v[206:209], v[194:197], v[114:117]
	v_mfma_f32_16x16x32_bf16 v[102:105], v[202:205], v[198:201], v[102:105]
	v_mfma_f32_16x16x32_bf16 v[106:109], v[206:209], v[198:201], v[106:109]
	ds_read_b128 v[118:121], v160 offset:768
	ds_read_b128 v[122:125], v160 offset:17408
	ds_read_b128 v[126:129], v226 offset:768
	s_and_saveexec_b64 s[24:25], s[8:9]
	ds_read_b128 v[130:133], v227 offset:768
	s_or_b64 exec, exec, s[24:25]
	s_waitcnt lgkmcnt(4)
	v_mfma_f32_16x16x32_bf16 v[110:113], v[218:221], v[210:213], v[110:113]
	v_mfma_f32_16x16x32_bf16 v[114:117], v[222:225], v[210:213], v[114:117]
	v_mfma_f32_16x16x32_bf16 v[102:105], v[218:221], v[214:217], v[102:105]
	v_mfma_f32_16x16x32_bf16 v[106:109], v[222:225], v[214:217], v[106:109]
	ds_read_b128 v[194:197], v160 offset:832
	ds_read_b128 v[198:201], v160 offset:17472
	ds_read_b128 v[202:205], v226 offset:832
	s_and_saveexec_b64 s[24:25], s[8:9]
	ds_read_b128 v[206:209], v227 offset:832
	s_or_b64 exec, exec, s[24:25]
	s_waitcnt lgkmcnt(4)
	v_mfma_f32_16x16x32_bf16 v[110:113], v[126:129], v[118:121], v[110:113]
	v_mfma_f32_16x16x32_bf16 v[114:117], v[130:133], v[118:121], v[114:117]
	v_mfma_f32_16x16x32_bf16 v[102:105], v[126:129], v[122:125], v[102:105]
	v_mfma_f32_16x16x32_bf16 v[106:109], v[130:133], v[122:125], v[106:109]
	ds_read_b128 v[210:213], v160 offset:896
	ds_read_b128 v[214:217], v160 offset:17536
	ds_read_b128 v[218:221], v226 offset:896
	s_and_saveexec_b64 s[24:25], s[8:9]
	ds_read_b128 v[222:225], v227 offset:896
	s_or_b64 exec, exec, s[24:25]
	s_waitcnt lgkmcnt(4)
	v_mfma_f32_16x16x32_bf16 v[110:113], v[202:205], v[194:197], v[110:113]
	v_mfma_f32_16x16x32_bf16 v[114:117], v[206:209], v[194:197], v[114:117]
	v_mfma_f32_16x16x32_bf16 v[102:105], v[202:205], v[198:201], v[102:105]
	v_mfma_f32_16x16x32_bf16 v[106:109], v[206:209], v[198:201], v[106:109]
	ds_read_b128 v[118:121], v160 offset:960
	ds_read_b128 v[122:125], v160 offset:17600
	ds_read_b128 v[126:129], v226 offset:960
	s_and_saveexec_b64 s[24:25], s[8:9]
	ds_read_b128 v[130:133], v227 offset:960
	s_or_b64 exec, exec, s[24:25]
	s_waitcnt lgkmcnt(4)
	v_mfma_f32_16x16x32_bf16 v[110:113], v[218:221], v[210:213], v[110:113]
	v_mfma_f32_16x16x32_bf16 v[114:117], v[222:225], v[210:213], v[114:117]
	v_mfma_f32_16x16x32_bf16 v[102:105], v[218:221], v[214:217], v[102:105]
	v_mfma_f32_16x16x32_bf16 v[106:109], v[222:225], v[214:217], v[106:109]
	ds_read_b128 v[194:197], v192
	ds_read_b128 v[198:201], v161
	ds_read_b128 v[202:205], v161 offset:2304
	ds_read_b128 v[206:209], v192 offset:64
	ds_read_b128 v[226:229], v161 offset:64
	ds_read_b128 v[230:233], v161 offset:2368
	s_waitcnt lgkmcnt(6)
	v_mfma_f32_16x16x32_bf16 v[110:113], v[126:129], v[118:121], v[110:113]
	v_mfma_f32_16x16x32_bf16 v[114:117], v[130:133], v[118:121], v[114:117]
	v_mfma_f32_16x16x32_bf16 v[102:105], v[126:129], v[122:125], v[102:105]
	v_mfma_f32_16x16x32_bf16 v[106:109], v[130:133], v[122:125], v[106:109]
	s_waitcnt lgkmcnt(4)
	v_mfma_f32_16x16x32_bf16 v[214:217], v[194:197], v[198:201], 0
	s_waitcnt lgkmcnt(3)
	v_mfma_f32_16x16x32_bf16 v[210:213], v[194:197], v[202:205], 0
	s_waitcnt lgkmcnt(1)
	v_mfma_f32_16x16x32_bf16 v[214:217], v[206:209], v[226:229], v[214:217]
	s_waitcnt lgkmcnt(0)
	v_mfma_f32_16x16x32_bf16 v[210:213], v[206:209], v[230:233], v[210:213]
	s_nop 1
	v_and_or_b32 v107, v234, 64, v154
	v_lshlrev_b32_e32 v107, 2, v107
	ds_bpermute_b32 v114, v107, v114
	ds_read2st64_b32 v[108:109], v173 offset1:2
	s_lshl_b32 s24, s30, 6
	s_add_i32 s24, s24, s18
	s_movk_i32 s31, 0x6000
	s_movk_i32 s34, 0x4000
	s_mov_b32 s35, 0x10000
	s_waitcnt lgkmcnt(0)
	v_fmac_f32_e32 v109, v108, v114
	v_max_f32_e64 v109, |v109|, 1.0
	v_rcp_f32_e32 v114, v109
	s_nop 2
	v_pk_fma_f32 v[110:111], v[110:111], v[108:109], v[214:215] op_sel_hi:[1,0,1]
	v_pk_fma_f32 v[108:109], v[112:113], v[108:109], v[216:217] op_sel_hi:[1,0,1]
	v_mul_f32_e64 v110, v110, v114
	v_mul_f32_e64 v111, v111, v114
	v_pk_mul_f32 v[108:109], v[108:109], v[114:115] op_sel_hi:[1,0]
	v_cvt_pk_bf16_f32 v110, v110, v111
	v_cvt_pk_bf16_f32 v111, v108, v109
	v_or_b32_e32 v108, s24, v155
	v_lshlrev_b32_e32 v108, 13, v108
	v_mov_b32_e32 v109, v0
	v_lshl_add_u64 v[108:109], v[150:151], 0, v[108:109]
	global_store_dwordx2 v[108:109], v[110:111], off
	ds_bpermute_b32 v108, v107, v106
	ds_read2st64_b32 v[106:107], v175 offset1:2
	s_waitcnt lgkmcnt(0)
	v_fmac_f32_e32 v107, v106, v108
	v_max_f32_e64 v107, |v107|, 1.0
	v_rcp_f32_e32 v108, v107
	v_pk_fma_f32 v[102:103], v[102:103], v[106:107], v[210:211] op_sel_hi:[1,0,1]
	v_pk_fma_f32 v[104:105], v[104:105], v[106:107], v[212:213] op_sel_hi:[1,0,1]
	v_pk_mul_f32 v[102:103], v[102:103], v[108:109] op_sel_hi:[1,0]
	v_pk_mul_f32 v[104:105], v[104:105], v[108:109] op_sel_hi:[1,0]
	v_cvt_pk_bf16_f32 v102, v102, v103
	v_cvt_pk_bf16_f32 v103, v104, v105
	v_or_b32_e32 v104, s24, v174
	v_lshlrev_b32_e32 v104, 13, v104
	v_mov_b32_e32 v105, v0
	v_lshl_add_u64 v[104:105], v[150:151], 0, v[104:105]
	global_store_dwordx2 v[104:105], v[102:103], off
